# P0 rmsnorm rows loop: wave reductions via DPP/permlane16_swap instead of ds_bpermute (xor 1..16 steps)
# speedup vs baseline: 1.0140x; 1.0140x over previous
.LBB0_63:
	v_pk_mul_f32 v[186:187], v[162:163], v[162:163]
	v_pk_mul_f32 v[200:201], v[164:165], v[164:165]
	v_pk_mul_f32 v[202:203], v[170:171], v[170:171]
	v_pk_mul_f32 v[204:205], v[172:173], v[172:173]
	v_mov_b32_e32 v206, v202
	v_mov_b32_e32 v207, v205
	v_pk_mov_b32 v[202:203], v[202:203], v[204:205] op_sel:[1,0]
	v_mov_b32_e32 v204, v186
	v_mov_b32_e32 v205, v201
	v_pk_mov_b32 v[186:187], v[186:187], v[200:201] op_sel:[1,0]
	v_pk_add_f32 v[202:203], v[202:203], v[206:207]
	v_pk_add_f32 v[186:187], v[186:187], v[204:205]
	v_pk_add_f32 v[202:203], v[202:203], v[202:203] op_sel_hi:[0,1]
	v_pk_add_f32 v[186:187], v[186:187], v[186:187] op_sel_hi:[0,1]
	v_mul_f32_e32 v186, v174, v174
	v_pk_fma_f32 v[200:201], v[174:175], v[174:175], v[186:187] op_sel_hi:[1,1,0]
	v_mul_f32_e32 v186, v176, v176
	v_pk_fma_f32 v[204:205], v[176:177], v[176:177], v[186:187] op_sel_hi:[1,1,0]
	v_mul_f32_e32 v200, v166, v166
	v_mul_f32_e32 v204, v167, v167
	v_mul_f32_e32 v202, v168, v168
	v_mul_f32_e32 v186, v169, v169
	v_pk_add_f32 v[200:201], v[200:201], v[204:205]
	v_pk_add_f32 v[186:187], v[202:203], v[186:187]
	s_nop 0
	v_pk_add_f32 v[186:187], v[200:201], v[186:187]
	s_nop 0
	v_add_f32_e32 v186, v186, v187
	s_waitcnt lgkmcnt(0)
	s_nop 1
	v_add_f32_dpp v186, v186, v186 quad_perm:[1,0,3,2] row_mask:0xf bank_mask:0xf
	s_waitcnt lgkmcnt(0)
	s_nop 1
	v_add_f32_dpp v186, v186, v186 quad_perm:[2,3,0,1] row_mask:0xf bank_mask:0xf
	s_waitcnt lgkmcnt(0)
	s_nop 1
	v_add_f32_dpp v187, v186, v186 row_shl:4 row_mask:0xf bank_mask:0x5
	v_add_f32_dpp v187, v186, v186 row_shr:4 row_mask:0xf bank_mask:0xa
	v_mov_b32_e32 v186, v187
	s_waitcnt lgkmcnt(0)
	s_nop 1
	v_add_f32_dpp v186, v186, v186 row_ror:8 row_mask:0xf bank_mask:0xf
	s_waitcnt lgkmcnt(0)
	v_mov_b32_e32 v187, v186
	s_nop 1
	v_permlane16_swap_b32_e32 v186, v187
	v_add_f32_e32 v186, v186, v187
	ds_bpermute_b32 v187, v193, v186
	s_waitcnt lgkmcnt(0)
	v_add_f32_e32 v186, v186, v187
	v_fmamk_f32 v186, v186, 0x3a800000, v179
	v_mul_f32_e32 v187, 0x4f800000, v186
	v_cmp_gt_f32_e32 vcc, s21, v186
	s_nop 1
	v_cndmask_b32_e32 v186, v186, v187, vcc
	v_sqrt_f32_e32 v187, v186
	s_nop 0
	v_add_u32_e32 v200, -1, v187
	v_add_u32_e32 v201, 1, v187
	v_fma_f32 v202, -v200, v187, v186
	v_fma_f32 v203, -v201, v187, v186
	v_cmp_ge_f32_e64 s[0:1], 0, v202
	s_nop 1
	v_cndmask_b32_e64 v187, v187, v200, s[0:1]
	v_cmp_lt_f32_e64 s[0:1], 0, v203
	s_nop 1
	v_cndmask_b32_e64 v187, v187, v201, s[0:1]
	v_mul_f32_e32 v200, 0x37800000, v187
	v_cndmask_b32_e32 v187, v187, v200, vcc
	v_cmp_class_f32_e32 vcc, v186, v194
	s_nop 1
	v_cndmask_b32_e32 v186, v187, v186, vcc
	v_div_scale_f32 v187, s[0:1], v186, v186, 1.0
	v_rcp_f32_e32 v200, v187
	v_div_scale_f32 v201, vcc, 1.0, v186, 1.0
	v_fma_f32 v202, -v187, v200, 1.0
	v_fmac_f32_e32 v200, v202, v200
	v_mul_f32_e32 v202, v201, v200
	v_fma_f32 v203, -v187, v202, v201
	v_fmac_f32_e32 v202, v203, v200
	v_fma_f32 v187, -v187, v202, v201
	v_div_fmas_f32 v187, v187, v200, v202
	v_div_fixup_f32 v200, v187, v186, 1.0
	v_pk_mul_f32 v[170:171], v[170:171], v[200:201] op_sel_hi:[1,0]
	v_pk_mul_f32 v[172:173], v[172:173], v[200:201] op_sel_hi:[1,0]
	v_pk_mul_f32 v[186:187], v[2:3], v[170:171]
	v_pk_mul_f32 v[172:173], v[4:5], v[172:173]
	v_and_b32_sdwa v202, v187, v196 dst_sel:DWORD dst_unused:UNUSED_PAD src0_sel:WORD_1 src1_sel:DWORD
	v_and_b32_sdwa v201, v173, v196 dst_sel:DWORD dst_unused:UNUSED_PAD src0_sel:WORD_1 src1_sel:DWORD
	v_and_b32_sdwa v170, v172, v196 dst_sel:DWORD dst_unused:UNUSED_PAD src0_sel:WORD_1 src1_sel:DWORD
	v_and_b32_sdwa v171, v186, v196 dst_sel:DWORD dst_unused:UNUSED_PAD src0_sel:WORD_1 src1_sel:DWORD
	v_add3_u32 v201, v173, v201, s44
	v_add3_u32 v202, v187, v202, s44
	v_add3_u32 v171, v186, v171, s44
	v_add3_u32 v170, v172, v170, s44
	v_and_b32_e32 v201, 0xffff0000, v201
	v_and_b32_e32 v202, 0xffff0000, v202
	v_or_b32_sdwa v203, v201, v170 dst_sel:DWORD dst_unused:UNUSED_PAD src0_sel:DWORD src1_sel:WORD_1
	v_or_b32_sdwa v202, v202, v171 dst_sel:DWORD dst_unused:UNUSED_PAD src0_sel:DWORD src1_sel:WORD_1
	v_lshl_add_u64 v[170:171], s[72:73], 0, v[184:185]
	v_add_co_u32_e32 v170, vcc, s45, v170
	v_mul_f32_e32 v207, v173, v69
	s_nop 0
	v_addc_co_u32_e32 v171, vcc, 0, v171, vcc
	global_store_dwordx2 v[170:171], v[202:203], off
	v_pk_mul_f32 v[202:203], v[162:163], v[200:201] op_sel_hi:[1,0]
	v_pk_mul_f32 v[162:163], v[164:165], v[200:201] op_sel_hi:[1,0]
	v_pk_mul_f32 v[164:165], v[6:7], v[202:203]
	v_pk_mul_f32 v[162:163], v[8:9], v[162:163]
	v_and_b32_sdwa v204, v165, v196 dst_sel:DWORD dst_unused:UNUSED_PAD src0_sel:WORD_1 src1_sel:DWORD
	v_and_b32_sdwa v203, v163, v196 dst_sel:DWORD dst_unused:UNUSED_PAD src0_sel:WORD_1 src1_sel:DWORD
	v_and_b32_sdwa v201, v162, v196 dst_sel:DWORD dst_unused:UNUSED_PAD src0_sel:WORD_1 src1_sel:DWORD
	v_and_b32_sdwa v202, v164, v196 dst_sel:DWORD dst_unused:UNUSED_PAD src0_sel:WORD_1 src1_sel:DWORD
	v_add3_u32 v203, v163, v203, s44
	v_add3_u32 v204, v165, v204, s44
	v_add3_u32 v202, v164, v202, s44
	v_add3_u32 v201, v162, v201, s44
	v_and_b32_e32 v203, 0xffff0000, v203
	v_and_b32_e32 v204, 0xffff0000, v204
	v_or_b32_sdwa v203, v203, v201 dst_sel:DWORD dst_unused:UNUSED_PAD src0_sel:DWORD src1_sel:WORD_1
	v_or_b32_sdwa v202, v204, v202 dst_sel:DWORD dst_unused:UNUSED_PAD src0_sel:DWORD src1_sel:WORD_1
	global_store_dwordx2 v[170:171], v[202:203], off offset:512
	v_pk_mul_f32 v[202:203], v[174:175], v[200:201] op_sel_hi:[1,0]
	v_pk_mul_f32 v[174:175], v[176:177], v[200:201] op_sel_hi:[1,0]
	v_pk_mul_f32 v[176:177], v[10:11], v[202:203]
	v_pk_mul_f32 v[174:175], v[12:13], v[174:175]
	v_and_b32_sdwa v204, v177, v196 dst_sel:DWORD dst_unused:UNUSED_PAD src0_sel:WORD_1 src1_sel:DWORD
	v_and_b32_sdwa v203, v175, v196 dst_sel:DWORD dst_unused:UNUSED_PAD src0_sel:WORD_1 src1_sel:DWORD
	v_and_b32_sdwa v201, v174, v196 dst_sel:DWORD dst_unused:UNUSED_PAD src0_sel:WORD_1 src1_sel:DWORD
	v_and_b32_sdwa v202, v176, v196 dst_sel:DWORD dst_unused:UNUSED_PAD src0_sel:WORD_1 src1_sel:DWORD
	v_add3_u32 v203, v175, v203, s44
	v_add3_u32 v204, v177, v204, s44
	v_add3_u32 v202, v176, v202, s44
	v_add3_u32 v201, v174, v201, s44
	v_and_b32_e32 v203, 0xffff0000, v203
	v_and_b32_e32 v204, 0xffff0000, v204
	v_or_b32_sdwa v203, v203, v201 dst_sel:DWORD dst_unused:UNUSED_PAD src0_sel:DWORD src1_sel:WORD_1
	v_or_b32_sdwa v202, v204, v202 dst_sel:DWORD dst_unused:UNUSED_PAD src0_sel:DWORD src1_sel:WORD_1
	v_pk_mul_f32 v[204:205], v[166:167], v[200:201] op_sel_hi:[1,0]
	v_pk_mul_f32 v[166:167], v[168:169], v[200:201] op_sel_hi:[1,0]
	v_mul_f32_e32 v200, v19, v187
	v_mul_f32_e32 v201, v21, v173
	v_fmac_f32_e32 v200, v18, v186
	v_fmac_f32_e32 v201, v20, v172
	v_pk_mul_f32 v[168:169], v[14:15], v[204:205]
	v_add_f32_e32 v200, v200, v201
	v_mul_f32_e32 v201, v23, v165
	v_mul_f32_e32 v204, v25, v163
	v_fmac_f32_e32 v201, v22, v164
	v_fmac_f32_e32 v204, v24, v162
	v_add_f32_e32 v200, 0, v200
	v_add_f32_e32 v201, v201, v204
	v_add_f32_e32 v200, v201, v200
	v_mul_f32_e32 v201, v27, v177
	v_mul_f32_e32 v204, v29, v175
	v_fmac_f32_e32 v201, v26, v176
	v_fmac_f32_e32 v204, v28, v174
	v_pk_mul_f32 v[166:167], v[16:17], v[166:167]
	v_add_f32_e32 v201, v201, v204
	v_add_f32_e32 v200, v201, v200
	v_mul_f32_e32 v201, v31, v169
	v_mul_f32_e32 v204, v33, v167
	v_fmac_f32_e32 v201, v30, v168
	v_fmac_f32_e32 v204, v32, v166
	v_add_f32_e32 v201, v201, v204
	v_mul_f32_e32 v204, v187, v35
	v_mul_f32_e32 v205, v173, v37
	v_fmac_f32_e32 v204, v186, v34
	v_fmac_f32_e32 v205, v172, v36
	v_add_f32_e32 v204, v204, v205
	v_mul_f32_e32 v205, v165, v39
	v_mul_f32_e32 v206, v163, v41
	v_fmac_f32_e32 v205, v164, v38
	v_fmac_f32_e32 v206, v162, v40
	v_add_f32_e32 v204, 0, v204
	v_add_f32_e32 v205, v205, v206
	v_add_f32_e32 v204, v204, v205
	v_mul_f32_e32 v205, v177, v43
	v_mul_f32_e32 v206, v175, v45
	v_fmac_f32_e32 v205, v176, v42
	v_fmac_f32_e32 v206, v174, v44
	v_add_f32_e32 v205, v205, v206
	v_add_f32_e32 v204, v204, v205
	v_mul_f32_e32 v205, v169, v47
	v_mul_f32_e32 v206, v167, v49
	v_fmac_f32_e32 v205, v168, v46
	v_fmac_f32_e32 v206, v166, v48
	v_add_f32_e32 v205, v205, v206
	v_add_f32_e32 v204, v204, v205
	global_store_dwordx2 v[170:171], v[202:203], off offset:1024
	v_and_b32_sdwa v202, v166, v196 dst_sel:DWORD dst_unused:UNUSED_PAD src0_sel:WORD_1 src1_sel:DWORD
	v_add3_u32 v211, v166, v202, s44
	v_and_b32_sdwa v202, v167, v196 dst_sel:DWORD dst_unused:UNUSED_PAD src0_sel:WORD_1 src1_sel:DWORD
	s_waitcnt lgkmcnt(0)
	s_nop 1
	v_add_f32_dpp v203, v204, v204 quad_perm:[1,0,3,2] row_mask:0xf bank_mask:0xf
	v_and_b32_sdwa v205, v168, v196 dst_sel:DWORD dst_unused:UNUSED_PAD src0_sel:WORD_1 src1_sel:DWORD
	v_add3_u32 v210, v168, v205, s44
	v_and_b32_sdwa v205, v169, v196 dst_sel:DWORD dst_unused:UNUSED_PAD src0_sel:WORD_1 src1_sel:DWORD
	v_add3_u32 v202, v167, v202, s44
	s_waitcnt lgkmcnt(0)
	s_nop 1
	v_add_f32_dpp v203, v203, v203 quad_perm:[2,3,0,1] row_mask:0xf bank_mask:0xf
	v_add3_u32 v212, v169, v205, s44
	v_and_b32_e32 v213, 0xffff0000, v202
	v_mul_f32_e32 v205, v173, v53
	v_fmac_f32_e32 v205, v172, v52
	s_waitcnt lgkmcnt(0)
	s_nop 1
	v_add_f32_dpp v204, v203, v203 row_shl:4 row_mask:0xf bank_mask:0x5
	v_add_f32_dpp v204, v203, v203 row_shr:4 row_mask:0xf bank_mask:0xa
	v_mov_b32_e32 v203, v204
	v_mul_f32_e32 v206, v163, v57
	v_fmac_f32_e32 v206, v162, v56
	v_fmac_f32_e32 v207, v172, v68
	v_mul_f32_e32 v208, v163, v73
	s_waitcnt lgkmcnt(0)
	s_nop 1
	v_add_f32_dpp v203, v203, v203 row_ror:8 row_mask:0xf bank_mask:0xf
	v_fmac_f32_e32 v208, v162, v72
	v_mul_f32_e32 v209, v173, v85
	v_fmac_f32_e32 v209, v172, v84
	v_mul_f32_e32 v214, v163, v89
	s_waitcnt lgkmcnt(0)
	v_mov_b32_e32 v204, v203
	s_nop 1
	v_permlane16_swap_b32_e32 v203, v204
	v_add_f32_e32 v202, v203, v204
	v_mul_f32_e32 v204, v187, v51
	v_fmac_f32_e32 v204, v186, v50
	v_add_f32_e32 v204, v204, v205
	v_mul_f32_e32 v205, v165, v55
	v_fmac_f32_e32 v205, v164, v54
	v_add_f32_e32 v204, 0, v204
	v_add_f32_e32 v205, v205, v206
	v_add_f32_e32 v204, v204, v205
	v_mul_f32_e32 v205, v177, v59
	v_mul_f32_e32 v206, v175, v61
	v_fmac_f32_e32 v205, v176, v58
	v_fmac_f32_e32 v206, v174, v60
	v_add_f32_e32 v205, v205, v206
	v_add_f32_e32 v204, v204, v205
	v_mul_f32_e32 v205, v169, v63
	v_mul_f32_e32 v206, v167, v65
	v_fmac_f32_e32 v205, v168, v62
	v_fmac_f32_e32 v206, v166, v64
	v_add_f32_e32 v205, v205, v206
	v_mul_f32_e32 v206, v187, v67
	v_fmac_f32_e32 v206, v186, v66
	v_add_f32_e32 v206, v206, v207
	v_mul_f32_e32 v207, v165, v71
	v_fmac_f32_e32 v207, v164, v70
	v_add_f32_e32 v206, 0, v206
	v_add_f32_e32 v207, v207, v208
	v_add_f32_e32 v206, v206, v207
	v_mul_f32_e32 v207, v177, v75
	v_mul_f32_e32 v208, v175, v77
	v_fmac_f32_e32 v207, v176, v74
	v_fmac_f32_e32 v208, v174, v76
	v_add_f32_e32 v207, v207, v208
	v_add_f32_e32 v206, v206, v207
	v_mul_f32_e32 v207, v169, v79
	v_mul_f32_e32 v208, v167, v81
	v_fmac_f32_e32 v207, v168, v78
	v_fmac_f32_e32 v208, v166, v80
	v_add_f32_e32 v207, v207, v208
	v_mul_f32_e32 v208, v187, v83
	v_fmac_f32_e32 v208, v186, v82
	v_add_f32_e32 v208, v208, v209
	v_mul_f32_e32 v209, v165, v87
	v_fmac_f32_e32 v209, v164, v86
	v_fmac_f32_e32 v214, v162, v88
	v_add_f32_e32 v208, 0, v208
	v_add_f32_e32 v209, v209, v214
	v_add_f32_e32 v208, v208, v209
	v_mul_f32_e32 v209, v177, v91
	v_mul_f32_e32 v214, v175, v93
	v_fmac_f32_e32 v209, v176, v90
	v_fmac_f32_e32 v214, v174, v92
	v_add_f32_e32 v209, v209, v214
	v_add_f32_e32 v208, v208, v209
	v_mul_f32_e32 v209, v169, v95
	v_mul_f32_e32 v214, v167, v97
	v_fmac_f32_e32 v209, v168, v94
	v_fmac_f32_e32 v214, v166, v96
	v_add_f32_e32 v209, v209, v214
	v_mul_f32_e32 v214, v187, v99
	v_mul_f32_e32 v215, v173, v101
	v_fmac_f32_e32 v214, v186, v98
	v_fmac_f32_e32 v215, v172, v100
	v_add_f32_e32 v214, v214, v215
	v_mul_f32_e32 v215, v165, v103
	v_mul_f32_e32 v216, v163, v105
	v_fmac_f32_e32 v215, v164, v102
	v_fmac_f32_e32 v216, v162, v104
	v_add_f32_e32 v214, 0, v214
	v_add_f32_e32 v215, v215, v216
	v_add_f32_e32 v214, v214, v215
	v_mul_f32_e32 v215, v177, v107
	v_mul_f32_e32 v216, v175, v109
	v_fmac_f32_e32 v215, v176, v106
	v_fmac_f32_e32 v216, v174, v108
	v_add_f32_e32 v215, v215, v216
	v_add_f32_e32 v214, v214, v215
	v_mul_f32_e32 v215, v169, v111
	v_mul_f32_e32 v216, v167, v113
	v_fmac_f32_e32 v215, v168, v110
	v_fmac_f32_e32 v216, v166, v112
	v_add_f32_e32 v215, v215, v216
	v_mul_f32_e32 v216, v187, v115
	v_mul_f32_e32 v217, v173, v117
	v_fmac_f32_e32 v216, v186, v114
	v_fmac_f32_e32 v217, v172, v116
	v_add_f32_e32 v216, v216, v217
	v_mul_f32_e32 v217, v165, v119
	v_mul_f32_e32 v218, v163, v121
	v_fmac_f32_e32 v217, v164, v118
	v_fmac_f32_e32 v218, v162, v120
	v_mul_f32_e32 v187, v187, v131
	v_mul_f32_e32 v173, v173, v133
	v_mul_f32_e32 v165, v165, v135
	v_mul_f32_e32 v163, v163, v137
	v_add_f32_e32 v216, 0, v216
	v_add_f32_e32 v217, v217, v218
	v_fmac_f32_e32 v187, v186, v130
	v_fmac_f32_e32 v173, v172, v132
	v_fmac_f32_e32 v165, v164, v134
	v_fmac_f32_e32 v163, v162, v136
	v_add_f32_e32 v216, v216, v217
	v_mul_f32_e32 v217, v177, v123
	v_mul_f32_e32 v218, v175, v125
	v_add_f32_e32 v172, v187, v173
	v_add_f32_e32 v162, v165, v163
	v_mul_f32_e32 v163, v177, v139
	v_mul_f32_e32 v164, v175, v141
	v_fmac_f32_e32 v217, v176, v122
	v_fmac_f32_e32 v218, v174, v124
	v_add_f32_e32 v172, 0, v172
	v_fmac_f32_e32 v163, v176, v138
	v_fmac_f32_e32 v164, v174, v140
	v_add_f32_e32 v217, v217, v218
	v_add_f32_e32 v162, v172, v162
	v_add_f32_e32 v163, v163, v164
	v_add_f32_e32 v216, v216, v217
	v_mul_f32_e32 v217, v169, v127
	v_mul_f32_e32 v218, v167, v129
	v_add_f32_e32 v162, v162, v163
	v_mul_f32_e32 v163, v169, v143
	v_mul_f32_e32 v164, v167, v145
	v_fmac_f32_e32 v217, v168, v126
	v_fmac_f32_e32 v218, v166, v128
	v_fmac_f32_e32 v163, v168, v142
	v_fmac_f32_e32 v164, v166, v144
	v_add_f32_e32 v217, v217, v218
	v_add_f32_e32 v163, v163, v164
	v_add_f32_e32 v200, v201, v200
	v_add_f32_e32 v204, v204, v205
	v_add_f32_e32 v206, v206, v207
	v_add_f32_e32 v208, v208, v209
	v_add_f32_e32 v214, v214, v215
	v_add_f32_e32 v216, v216, v217
	v_add_f32_e32 v162, v162, v163
	s_waitcnt lgkmcnt(6)
	s_nop 1
	v_add_f32_dpp v200, v200, v200 quad_perm:[1,0,3,2] row_mask:0xf bank_mask:0xf
	s_waitcnt lgkmcnt(5)
	s_nop 1
	v_add_f32_dpp v204, v204, v204 quad_perm:[1,0,3,2] row_mask:0xf bank_mask:0xf
	s_waitcnt lgkmcnt(4)
	s_nop 1
	v_add_f32_dpp v206, v206, v206 quad_perm:[1,0,3,2] row_mask:0xf bank_mask:0xf
	s_waitcnt lgkmcnt(3)
	s_nop 1
	v_add_f32_dpp v208, v208, v208 quad_perm:[1,0,3,2] row_mask:0xf bank_mask:0xf
	s_waitcnt lgkmcnt(2)
	s_nop 1
	v_add_f32_dpp v164, v214, v214 quad_perm:[1,0,3,2] row_mask:0xf bank_mask:0xf
	s_waitcnt lgkmcnt(1)
	s_nop 1
	v_add_f32_dpp v166, v216, v216 quad_perm:[1,0,3,2] row_mask:0xf bank_mask:0xf
	s_waitcnt lgkmcnt(0)
	s_nop 1
	v_add_f32_dpp v162, v162, v162 quad_perm:[1,0,3,2] row_mask:0xf bank_mask:0xf
	s_waitcnt lgkmcnt(6)
	s_nop 1
	v_add_f32_dpp v200, v200, v200 quad_perm:[2,3,0,1] row_mask:0xf bank_mask:0xf
	s_waitcnt lgkmcnt(5)
	s_nop 1
	v_add_f32_dpp v204, v204, v204 quad_perm:[2,3,0,1] row_mask:0xf bank_mask:0xf
	s_waitcnt lgkmcnt(4)
	s_nop 1
	v_add_f32_dpp v206, v206, v206 quad_perm:[2,3,0,1] row_mask:0xf bank_mask:0xf
	s_waitcnt lgkmcnt(3)
	s_nop 1
	v_add_f32_dpp v208, v208, v208 quad_perm:[2,3,0,1] row_mask:0xf bank_mask:0xf
	s_waitcnt lgkmcnt(2)
	s_nop 1
	v_add_f32_dpp v164, v164, v164 quad_perm:[2,3,0,1] row_mask:0xf bank_mask:0xf
	s_waitcnt lgkmcnt(1)
	s_nop 1
	v_add_f32_dpp v166, v166, v166 quad_perm:[2,3,0,1] row_mask:0xf bank_mask:0xf
	s_waitcnt lgkmcnt(0)
	s_nop 1
	v_add_f32_dpp v162, v162, v162 quad_perm:[2,3,0,1] row_mask:0xf bank_mask:0xf
	s_waitcnt lgkmcnt(6)
	s_nop 1
	v_add_f32_dpp v201, v200, v200 row_shl:4 row_mask:0xf bank_mask:0x5
	v_add_f32_dpp v201, v200, v200 row_shr:4 row_mask:0xf bank_mask:0xa
	v_mov_b32_e32 v200, v201
	s_waitcnt lgkmcnt(5)
	s_nop 1
	v_add_f32_dpp v205, v204, v204 row_shl:4 row_mask:0xf bank_mask:0x5
	v_add_f32_dpp v205, v204, v204 row_shr:4 row_mask:0xf bank_mask:0xa
	v_mov_b32_e32 v204, v205
	s_waitcnt lgkmcnt(4)
	s_nop 1
	v_add_f32_dpp v207, v206, v206 row_shl:4 row_mask:0xf bank_mask:0x5
	v_add_f32_dpp v207, v206, v206 row_shr:4 row_mask:0xf bank_mask:0xa
	v_mov_b32_e32 v206, v207
	s_waitcnt lgkmcnt(3)
	s_nop 1
	v_add_f32_dpp v209, v208, v208 row_shl:4 row_mask:0xf bank_mask:0x5
	v_add_f32_dpp v209, v208, v208 row_shr:4 row_mask:0xf bank_mask:0xa
	v_mov_b32_e32 v208, v209
	s_waitcnt lgkmcnt(2)
	s_nop 1
	v_add_f32_dpp v165, v164, v164 row_shl:4 row_mask:0xf bank_mask:0x5
	v_add_f32_dpp v165, v164, v164 row_shr:4 row_mask:0xf bank_mask:0xa
	v_mov_b32_e32 v164, v165
	s_waitcnt lgkmcnt(1)
	s_nop 1
	v_add_f32_dpp v167, v166, v166 row_shl:4 row_mask:0xf bank_mask:0x5
	v_add_f32_dpp v167, v166, v166 row_shr:4 row_mask:0xf bank_mask:0xa
	v_mov_b32_e32 v166, v167
	s_waitcnt lgkmcnt(0)
	s_nop 1
	v_add_f32_dpp v163, v162, v162 row_shl:4 row_mask:0xf bank_mask:0x5
	v_add_f32_dpp v163, v162, v162 row_shr:4 row_mask:0xf bank_mask:0xa
	v_mov_b32_e32 v162, v163
	s_waitcnt lgkmcnt(6)
	s_nop 1
	v_add_f32_dpp v200, v200, v200 row_ror:8 row_mask:0xf bank_mask:0xf
	s_waitcnt lgkmcnt(5)
	s_nop 1
	v_add_f32_dpp v204, v204, v204 row_ror:8 row_mask:0xf bank_mask:0xf
	s_waitcnt lgkmcnt(4)
	s_nop 1
	v_add_f32_dpp v206, v206, v206 row_ror:8 row_mask:0xf bank_mask:0xf
	s_waitcnt lgkmcnt(3)
	s_nop 1
	v_add_f32_dpp v208, v208, v208 row_ror:8 row_mask:0xf bank_mask:0xf
	s_waitcnt lgkmcnt(2)
	s_nop 1
	v_add_f32_dpp v164, v164, v164 row_ror:8 row_mask:0xf bank_mask:0xf
	s_waitcnt lgkmcnt(1)
	s_nop 1
	v_add_f32_dpp v166, v166, v166 row_ror:8 row_mask:0xf bank_mask:0xf
	s_waitcnt lgkmcnt(0)
	s_nop 1
	v_add_f32_dpp v168, v162, v162 row_ror:8 row_mask:0xf bank_mask:0xf
	s_waitcnt lgkmcnt(6)
	v_mov_b32_e32 v201, v200
	s_nop 1
	v_permlane16_swap_b32_e32 v200, v201
	v_add_f32_e32 v200, v200, v201
	s_waitcnt lgkmcnt(5)
	v_mov_b32_e32 v205, v204
	s_nop 1
	v_permlane16_swap_b32_e32 v204, v205
	v_add_f32_e32 v204, v204, v205
	s_waitcnt lgkmcnt(4)
	v_mov_b32_e32 v207, v206
	s_nop 1
	v_permlane16_swap_b32_e32 v206, v207
	v_add_f32_e32 v206, v206, v207
	s_waitcnt lgkmcnt(3)
	v_mov_b32_e32 v209, v208
	s_nop 1
	v_permlane16_swap_b32_e32 v208, v209
	v_add_f32_e32 v208, v208, v209
	s_waitcnt lgkmcnt(2)
	v_mov_b32_e32 v165, v164
	s_nop 1
	v_permlane16_swap_b32_e32 v164, v165
	v_add_f32_e32 v162, v164, v165
	s_waitcnt lgkmcnt(1)
	v_mov_b32_e32 v167, v166
	s_nop 1
	v_permlane16_swap_b32_e32 v166, v167
	v_add_f32_e32 v164, v166, v167
	s_waitcnt lgkmcnt(0)
	v_mov_b32_e32 v169, v168
	s_nop 1
	v_permlane16_swap_b32_e32 v168, v169
	v_add_f32_e32 v166, v168, v169
	ds_bpermute_b32 v201, v193, v200
	ds_bpermute_b32 v203, v193, v202
	ds_bpermute_b32 v205, v193, v204
	ds_bpermute_b32 v207, v193, v206
	ds_bpermute_b32 v209, v193, v208
	ds_bpermute_b32 v163, v193, v162
	ds_bpermute_b32 v165, v193, v164
	ds_bpermute_b32 v167, v193, v166
	v_and_b32_e32 v168, 0xffff0000, v212
	v_or_b32_sdwa v169, v213, v211 dst_sel:DWORD dst_unused:UNUSED_PAD src0_sel:DWORD src1_sel:WORD_1
	v_or_b32_sdwa v168, v168, v210 dst_sel:DWORD dst_unused:UNUSED_PAD src0_sel:DWORD src1_sel:WORD_1
	global_store_dwordx2 v[170:171], v[168:169], off offset:1536
	s_and_saveexec_b64 s[0:1], s[2:3]
	s_cbranch_execz .LBB0_42
	s_waitcnt lgkmcnt(7)
	v_add_f32_e32 v169, v200, v201
	s_waitcnt lgkmcnt(6)
	v_add_f32_e32 v168, v202, v203
	v_cndmask_b32_e64 v169, 0, v169, s[18:19]
	s_waitcnt lgkmcnt(0)
	v_add_f32_e32 v166, v166, v167
	v_add_f32_e32 v167, v204, v205
	v_cndmask_b32_e64 v168, v169, v168, s[16:17]
	v_add_f32_e32 v164, v164, v165
	v_add_f32_e32 v165, v206, v207
	v_cndmask_b32_e64 v167, v168, v167, s[14:15]
	v_add_f32_e32 v162, v162, v163
	v_add_f32_e32 v163, v208, v209
	v_cndmask_b32_e64 v165, v167, v165, s[12:13]
	v_cndmask_b32_e64 v163, v165, v163, s[10:11]
	v_cndmask_b32_e64 v162, v163, v162, s[8:9]
	v_cndmask_b32_e64 v162, v162, v164, s[6:7]
	v_cndmask_b32_e64 v162, v162, v166, s[4:5]
	v_add_f32_e32 v162, v181, v162
	v_mul_f32_e64 v163, |v162|, s46
	v_exp_f32_e32 v164, v163
	v_min_f32_e32 v165, 0, v162
	s_cmp_lg_u64 s[22:23], 0
	v_add_f32_e32 v166, 1.0, v164
	v_add_f32_e32 v162, -1.0, v166
	v_sub_f32_e32 v163, v162, v166
	v_add_f32_e32 v163, 1.0, v163
	v_sub_f32_e32 v162, v164, v162
	v_add_f32_e32 v167, v162, v163
	v_frexp_mant_f32_e32 v168, v166
	v_cvt_f64_f32_e32 v[162:163], v166
	v_frexp_exp_i32_f64_e32 v162, v[162:163]
	v_cmp_gt_f32_e32 vcc, s47, v168
	s_nop 1
	v_subbrev_co_u32_e32 v162, vcc, 0, v162, vcc
	v_sub_u32_e32 v163, 0, v162
	v_ldexp_f32 v166, v166, v163
	v_ldexp_f32 v163, v167, v163
	v_add_f32_e32 v167, -1.0, v166
	v_add_f32_e32 v170, 1.0, v166
	v_add_f32_e32 v168, 1.0, v167
	v_add_f32_e32 v171, -1.0, v170
	v_sub_f32_e32 v168, v166, v168
	v_sub_f32_e32 v166, v166, v171
	v_add_f32_e32 v168, v163, v168
	v_add_f32_e32 v163, v163, v166
	v_add_f32_e32 v166, v170, v163
	v_rcp_f32_e32 v171, v166
	v_add_f32_e32 v169, v167, v168
	v_sub_f32_e32 v167, v169, v167
	v_sub_f32_e32 v167, v168, v167
	v_sub_f32_e32 v168, v166, v170
	v_sub_f32_e32 v163, v163, v168
	v_mul_f32_e32 v168, v169, v171
	v_mul_f32_e32 v170, v166, v168
	v_fma_f32 v172, v168, v166, -v170
	v_fmac_f32_e32 v172, v168, v163
	v_add_f32_e32 v173, v170, v172
	v_sub_f32_e32 v174, v169, v173
	v_sub_f32_e32 v169, v169, v174
	v_sub_f32_e32 v170, v173, v170
	v_sub_f32_e32 v169, v169, v173
	v_add_f32_e32 v167, v167, v169
	v_sub_f32_e32 v169, v170, v172
	v_add_f32_e32 v167, v169, v167
	v_add_f32_e32 v169, v174, v167
	v_mul_f32_e32 v170, v171, v169
	v_mul_f32_e32 v172, v166, v170
	v_fma_f32 v166, v170, v166, -v172
	v_fmac_f32_e32 v166, v170, v163
	v_sub_f32_e32 v163, v174, v169
	v_add_f32_e32 v163, v167, v163
	v_add_f32_e32 v167, v172, v166
	v_sub_f32_e32 v173, v169, v167
	v_sub_f32_e32 v169, v169, v173
	v_sub_f32_e32 v172, v167, v172
	v_sub_f32_e32 v167, v169, v167
	v_add_f32_e32 v163, v163, v167
	v_sub_f32_e32 v166, v172, v166
	v_cvt_f32_i32_e32 v162, v162
	v_add_f32_e32 v163, v166, v163
	v_add_f32_e32 v166, v168, v170
	v_add_f32_e32 v163, v173, v163
	v_sub_f32_e32 v167, v166, v168
	v_mul_f32_e32 v163, v171, v163
	v_sub_f32_e32 v167, v170, v167
	v_add_f32_e32 v163, v167, v163
	v_mul_f32_e32 v170, 0x3f317218, v162
	v_add_f32_e32 v167, v166, v163
	v_fma_f32 v171, v162, s48, -v170
	v_mul_f32_e32 v168, v167, v167
	v_fmac_f32_e32 v171, 0xb102e308, v162
	v_sub_f32_e32 v162, v167, v166
	v_fmamk_f32 v169, v168, 0x3e9b6dac, v195
	v_sub_f32_e32 v162, v163, v162
	v_add_f32_e32 v163, v170, v171
	v_fmaak_f32 v169, v168, v169, 0x3f2aaada
	v_sub_f32_e32 v166, v163, v170
	v_ldexp_f32 v170, v167, 1
	v_mul_f32_e32 v167, v167, v168
	v_mul_f32_e32 v167, v167, v169
	v_add_f32_e32 v168, v170, v167
	v_sub_f32_e32 v169, v168, v170
	v_ldexp_f32 v162, v162, 1
	v_sub_f32_e32 v167, v167, v169
	v_add_f32_e32 v162, v162, v167
	v_add_f32_e32 v167, v168, v162
	v_sub_f32_e32 v168, v167, v168
	v_sub_f32_e32 v162, v162, v168
	v_add_f32_e32 v168, v163, v167
	v_sub_f32_e32 v169, v168, v163
	v_sub_f32_e32 v170, v168, v169
	v_sub_f32_e32 v166, v171, v166
	v_sub_f32_e32 v163, v163, v170
	v_sub_f32_e32 v167, v167, v169
	v_add_f32_e32 v163, v167, v163
	v_add_f32_e32 v167, v166, v162
	v_sub_f32_e32 v169, v167, v166
	v_sub_f32_e32 v170, v167, v169
	v_sub_f32_e32 v166, v166, v170
	v_sub_f32_e32 v162, v162, v169
	v_add_f32_e32 v163, v167, v163
	v_add_f32_e32 v162, v162, v166
	v_add_f32_e32 v166, v168, v163
	v_sub_f32_e32 v167, v166, v168
	v_sub_f32_e32 v163, v163, v167
	v_add_f32_e32 v162, v162, v163
	v_add_f32_e32 v162, v166, v162
	v_cmp_neq_f32_e32 vcc, s49, v164
	s_nop 1
	v_cndmask_b32_e32 v162, v197, v162, vcc
	v_cmp_ngt_f32_e32 vcc, -1.0, v164
	s_nop 1
	v_cndmask_b32_e32 v162, v198, v162, vcc
	v_cmp_neq_f32_e32 vcc, -1.0, v164
	s_nop 1
	v_cndmask_b32_e32 v162, v199, v162, vcc
	v_cmp_lt_f32_e64 vcc, |v164|, s50
	s_nop 1
	v_cndmask_b32_e32 v162, v162, v164, vcc
	v_sub_f32_e32 v162, v165, v162
	s_cselect_b64 vcc, -1, 0
	v_cndmask_b32_e32 v162, 0, v162, vcc
	v_lshl_add_u64 v[164:165], s[72:73], 0, v[182:183]
	s_cmp_eq_u64 s[30:31], 0
	global_store_dword v[164:165], v162, off
	s_cbranch_scc1 .LBB0_42
	global_store_dword v178, v162, s[30:31]
	s_branch .LBB0_42

.Lpost_getpc1:
	s_add_u32 s98, s98, (.LBB0_930-.Lpost_getpc1)&4294967295
	s_addc_u32 s99, s99, (.LBB0_930-.Lpost_getpc1)>>32
	s_setpc_b64 s[98:99]
	s_nop 0
	s_nop 0
	s_nop 0
	s_nop 0
	s_nop 0
	s_nop 0
	s_nop 0
	s_nop 0
	s_nop 0
	s_nop 0
	s_nop 0
	s_nop 0
	s_nop 0
	s_nop 0
	s_nop 0
	s_nop 0
	s_nop 0
	s_nop 0
	s_nop 0
	s_nop 0
	s_nop 0
	s_nop 0
	s_nop 0
	s_nop 0
	s_nop 0
	s_nop 0
	s_nop 0
	s_nop 0
